# v23: v21 + grid barriers 2..6 issue the census loads and the arrival atomic together (one round trip, no census poll)
# baseline (speedup 1.0000x reference)
.LBB0_281:
	global_load_dword v15, v16, s[70:71] offset:1024 sc1
	global_load_dword v0, v16, s[70:71] offset:1280 sc1
	global_load_dword v1, v16, s[70:71] offset:1536 sc1
	global_load_dword v2, v16, s[70:71] offset:1792 sc1
	global_load_dword v3, v16, s[70:71] offset:2048 sc1
	global_load_dword v4, v16, s[70:71] offset:2304 sc1
	global_load_dword v5, v16, s[70:71] offset:2560 sc1
	global_load_dword v6, v16, s[70:71] offset:2816 sc1
	global_load_dword v7, v16, s[70:71] offset:3072 sc1
	global_load_dword v8, v16, s[70:71] offset:3328 sc1
	global_load_dword v9, v16, s[70:71] offset:3584 sc1
	global_load_dword v10, v16, s[70:71] offset:3840 sc1
	global_load_dword v11, v16, s[6:7] sc1
	global_load_dword v12, v16, s[8:9] sc1
	global_load_dword v13, v16, s[10:11] sc1
	global_load_dword v14, v16, s[28:29] sc1
	s_mov_b64 s[8:9], exec
	s_and_b32 s0, s0, 15
	s_lshl_b32 s1, s0, 8
	v_mbcnt_lo_u32_b32 v16, s8, 0
	s_add_u32 s6, s70, s1
	v_mbcnt_hi_u32_b32 v16, s9, v16
	s_addc_u32 s7, s71, 0
	v_cmp_eq_u32_e32 vcc, 0, v16
	s_and_saveexec_b64 s[10:11], vcc
	s_cbranch_execz .LBB0_285
	s_bcnt1_i32_b64 s1, s[8:9]
	v_mov_b32_e32 v17, 0x1000
	v_mov_b32_e32 v18, s1
	global_atomic_add v17, v17, v18, s[6:7] offset:1024 sc0
.LBB0_285:
	s_or_b64 exec, exec, s[10:11]
	s_waitcnt vmcnt(0)
	s_cmp_eq_u32 s0, 0
	s_cselect_b64 vcc, -1, 0
	s_cmp_eq_u32 s0, 1
	v_cndmask_b32_e32 v18, 1, v15, vcc
	s_cselect_b64 vcc, -1, 0
	s_cmp_eq_u32 s0, 2
	v_cndmask_b32_e32 v18, v18, v0, vcc
	s_cselect_b64 vcc, -1, 0
	s_cmp_eq_u32 s0, 3
	v_cndmask_b32_e32 v18, v18, v1, vcc
	s_cselect_b64 vcc, -1, 0
	s_cmp_eq_u32 s0, 4
	v_cndmask_b32_e32 v18, v18, v2, vcc
	s_cselect_b64 vcc, -1, 0
	s_cmp_eq_u32 s0, 5
	v_cndmask_b32_e32 v18, v18, v3, vcc
	s_cselect_b64 vcc, -1, 0
	s_cmp_eq_u32 s0, 6
	v_cndmask_b32_e32 v18, v18, v4, vcc
	s_cselect_b64 vcc, -1, 0
	s_cmp_eq_u32 s0, 7
	v_cndmask_b32_e32 v18, v18, v5, vcc
	s_cselect_b64 vcc, -1, 0
	s_cmp_eq_u32 s0, 8
	v_cndmask_b32_e32 v18, v18, v6, vcc
	s_cselect_b64 vcc, -1, 0
	s_cmp_eq_u32 s0, 9
	v_cndmask_b32_e32 v18, v18, v7, vcc
	s_cselect_b64 vcc, -1, 0
	s_cmp_eq_u32 s0, 10
	v_cndmask_b32_e32 v18, v18, v8, vcc
	s_cselect_b64 vcc, -1, 0
	s_cmp_eq_u32 s0, 11
	v_cndmask_b32_e32 v18, v18, v9, vcc
	s_cselect_b64 vcc, -1, 0
	s_cmp_eq_u32 s0, 12
	v_cndmask_b32_e32 v18, v18, v10, vcc
	s_cselect_b64 vcc, -1, 0
	s_cmp_eq_u32 s0, 13
	v_cndmask_b32_e32 v18, v18, v11, vcc
	s_cselect_b64 vcc, -1, 0
	s_cmp_eq_u32 s0, 14
	v_cndmask_b32_e32 v18, v18, v12, vcc
	s_cselect_b64 vcc, -1, 0
	s_cmp_eq_u32 s0, 15
	v_cndmask_b32_e32 v18, v18, v13, vcc
	s_cselect_b64 vcc, -1, 0
	v_cndmask_b32_e32 v18, v18, v14, vcc
	v_cvt_f32_u32_e32 v19, v18
	s_waitcnt vmcnt(0)
	v_readfirstlane_b32 s0, v17
	v_rcp_iflag_f32_e32 v19, v19
	s_nop 0
	v_add_u32_e32 v17, s0, v16
	v_sub_u32_e32 v16, 0, v18
	v_mul_f32_e32 v19, 0x4f7ffffe, v19
	v_cvt_u32_f32_e32 v19, v19
	v_mul_lo_u32 v16, v16, v19
	v_mul_hi_u32 v16, v19, v16
	v_add_u32_e32 v16, v19, v16
	v_mul_hi_u32 v16, v17, v16
	v_mul_lo_u32 v19, v16, v18
	v_sub_u32_e32 v19, v17, v19
	v_add_u32_e32 v20, 1, v16
	v_cmp_ge_u32_e32 vcc, v19, v18
	v_add_u32_e32 v17, 1, v17
	s_nop 0
	v_cndmask_b32_e32 v16, v16, v20, vcc
	v_sub_u32_e32 v20, v19, v18
	v_cndmask_b32_e32 v19, v19, v20, vcc
	v_add_u32_e32 v20, 1, v16
	v_cmp_ge_u32_e32 vcc, v19, v18
	s_nop 1
	v_cndmask_b32_e32 v16, v16, v20, vcc
	v_mul_lo_u32 v19, v18, v16
	v_add_u32_e32 v18, v19, v18
	v_cmp_ne_u32_e32 vcc, v17, v18
	s_and_saveexec_b64 s[0:1], vcc
	s_xor_b64 s[8:9], exec, s[0:1]
	s_cbranch_execz .LBB0_290
	v_mov_b32_e32 v17, 0x2000
	global_load_dword v17, v17, s[6:7] offset:1024 sc1
	s_add_u32 s10, s6, 0x2400
	s_addc_u32 s11, s7, 0
	s_waitcnt vmcnt(0)
	v_cmp_eq_u32_e32 vcc, v17, v16
	s_and_saveexec_b64 s[28:29], vcc
	s_cbranch_execz .LBB0_289
	s_mov_b64 s[30:31], 0
	v_mov_b32_e32 v17, 0

.LBB0_565:
	global_load_dword v15, v16, s[70:71] offset:1024 sc1
	global_load_dword v0, v16, s[70:71] offset:1280 sc1
	global_load_dword v1, v16, s[70:71] offset:1536 sc1
	global_load_dword v2, v16, s[70:71] offset:1792 sc1
	global_load_dword v3, v16, s[70:71] offset:2048 sc1
	global_load_dword v4, v16, s[70:71] offset:2304 sc1
	global_load_dword v5, v16, s[70:71] offset:2560 sc1
	global_load_dword v6, v16, s[70:71] offset:2816 sc1
	global_load_dword v7, v16, s[70:71] offset:3072 sc1
	global_load_dword v8, v16, s[70:71] offset:3328 sc1
	global_load_dword v9, v16, s[70:71] offset:3584 sc1
	global_load_dword v10, v16, s[70:71] offset:3840 sc1
	global_load_dword v11, v16, s[6:7] sc1
	global_load_dword v12, v16, s[8:9] sc1
	global_load_dword v13, v16, s[10:11] sc1
	global_load_dword v14, v16, s[12:13] sc1
	s_mov_b64 s[8:9], exec
	s_and_b32 s0, s0, 15
	s_lshl_b32 s1, s0, 8
	v_mbcnt_lo_u32_b32 v16, s8, 0
	s_add_u32 s6, s70, s1
	v_mbcnt_hi_u32_b32 v16, s9, v16
	s_addc_u32 s7, s71, 0
	v_cmp_eq_u32_e32 vcc, 0, v16
	s_and_saveexec_b64 s[10:11], vcc
	s_cbranch_execz .LBB0_569
	s_bcnt1_i32_b64 s1, s[8:9]
	v_mov_b32_e32 v17, 0x1000
	v_mov_b32_e32 v18, s1
	global_atomic_add v17, v17, v18, s[6:7] offset:1024 sc0
.LBB0_569:
	s_or_b64 exec, exec, s[10:11]
	s_waitcnt vmcnt(0)
	s_cmp_eq_u32 s0, 0
	s_cselect_b64 vcc, -1, 0
	s_cmp_eq_u32 s0, 1
	v_cndmask_b32_e32 v18, 1, v15, vcc
	s_cselect_b64 vcc, -1, 0
	s_cmp_eq_u32 s0, 2
	v_cndmask_b32_e32 v18, v18, v0, vcc
	s_cselect_b64 vcc, -1, 0
	s_cmp_eq_u32 s0, 3
	v_cndmask_b32_e32 v18, v18, v1, vcc
	s_cselect_b64 vcc, -1, 0
	s_cmp_eq_u32 s0, 4
	v_cndmask_b32_e32 v18, v18, v2, vcc
	s_cselect_b64 vcc, -1, 0
	s_cmp_eq_u32 s0, 5
	v_cndmask_b32_e32 v18, v18, v3, vcc
	s_cselect_b64 vcc, -1, 0
	s_cmp_eq_u32 s0, 6
	v_cndmask_b32_e32 v18, v18, v4, vcc
	s_cselect_b64 vcc, -1, 0
	s_cmp_eq_u32 s0, 7
	v_cndmask_b32_e32 v18, v18, v5, vcc
	s_cselect_b64 vcc, -1, 0
	s_cmp_eq_u32 s0, 8
	v_cndmask_b32_e32 v18, v18, v6, vcc
	s_cselect_b64 vcc, -1, 0
	s_cmp_eq_u32 s0, 9
	v_cndmask_b32_e32 v18, v18, v7, vcc
	s_cselect_b64 vcc, -1, 0
	s_cmp_eq_u32 s0, 10
	v_cndmask_b32_e32 v18, v18, v8, vcc
	s_cselect_b64 vcc, -1, 0
	s_cmp_eq_u32 s0, 11
	v_cndmask_b32_e32 v18, v18, v9, vcc
	s_cselect_b64 vcc, -1, 0
	s_cmp_eq_u32 s0, 12
	v_cndmask_b32_e32 v18, v18, v10, vcc
	s_cselect_b64 vcc, -1, 0
	s_cmp_eq_u32 s0, 13
	v_cndmask_b32_e32 v18, v18, v11, vcc
	s_cselect_b64 vcc, -1, 0
	s_cmp_eq_u32 s0, 14
	v_cndmask_b32_e32 v18, v18, v12, vcc
	s_cselect_b64 vcc, -1, 0
	s_cmp_eq_u32 s0, 15
	v_cndmask_b32_e32 v18, v18, v13, vcc
	s_cselect_b64 vcc, -1, 0
	v_cndmask_b32_e32 v18, v18, v14, vcc
	v_cvt_f32_u32_e32 v19, v18
	s_waitcnt vmcnt(0)
	v_readfirstlane_b32 s0, v17
	v_rcp_iflag_f32_e32 v19, v19
	s_nop 0
	v_add_u32_e32 v17, s0, v16
	v_sub_u32_e32 v16, 0, v18
	v_mul_f32_e32 v19, 0x4f7ffffe, v19
	v_cvt_u32_f32_e32 v19, v19
	v_mul_lo_u32 v16, v16, v19
	v_mul_hi_u32 v16, v19, v16
	v_add_u32_e32 v16, v19, v16
	v_mul_hi_u32 v16, v17, v16
	v_mul_lo_u32 v19, v16, v18
	v_sub_u32_e32 v19, v17, v19
	v_add_u32_e32 v20, 1, v16
	v_cmp_ge_u32_e32 vcc, v19, v18
	v_add_u32_e32 v17, 1, v17
	s_nop 0
	v_cndmask_b32_e32 v16, v16, v20, vcc
	v_sub_u32_e32 v20, v19, v18
	v_cndmask_b32_e32 v19, v19, v20, vcc
	v_add_u32_e32 v20, 1, v16
	v_cmp_ge_u32_e32 vcc, v19, v18
	s_nop 1
	v_cndmask_b32_e32 v16, v16, v20, vcc
	v_mul_lo_u32 v19, v18, v16
	v_add_u32_e32 v18, v19, v18
	v_cmp_ne_u32_e32 vcc, v17, v18
	s_and_saveexec_b64 s[0:1], vcc
	s_xor_b64 s[8:9], exec, s[0:1]
	s_cbranch_execz .LBB0_574
	v_mov_b32_e32 v17, 0x2000
	global_load_dword v17, v17, s[6:7] offset:1024 sc1
	s_add_u32 s10, s6, 0x2400
	s_addc_u32 s11, s7, 0
	s_waitcnt vmcnt(0)
	v_cmp_eq_u32_e32 vcc, v17, v16
	s_and_saveexec_b64 s[12:13], vcc
	s_cbranch_execz .LBB0_573
	s_mov_b64 s[14:15], 0
	v_mov_b32_e32 v17, 0

.LBB0_1399:
	global_load_dword v15, v16, s[70:71] offset:1024 sc1
	global_load_dword v0, v16, s[70:71] offset:1280 sc1
	global_load_dword v1, v16, s[70:71] offset:1536 sc1
	global_load_dword v2, v16, s[70:71] offset:1792 sc1
	global_load_dword v3, v16, s[70:71] offset:2048 sc1
	global_load_dword v4, v16, s[70:71] offset:2304 sc1
	global_load_dword v5, v16, s[70:71] offset:2560 sc1
	global_load_dword v6, v16, s[70:71] offset:2816 sc1
	global_load_dword v7, v16, s[70:71] offset:3072 sc1
	global_load_dword v8, v16, s[70:71] offset:3328 sc1
	global_load_dword v9, v16, s[70:71] offset:3584 sc1
	global_load_dword v10, v16, s[70:71] offset:3840 sc1
	global_load_dword v11, v16, s[8:9] sc1
	global_load_dword v12, v16, s[10:11] sc1
	global_load_dword v13, v16, s[12:13] sc1
	global_load_dword v14, v16, s[14:15] sc1
	s_mov_b64 s[10:11], exec
	s_and_b32 s0, s0, 15
	s_lshl_b32 s1, s0, 8
	v_mbcnt_lo_u32_b32 v16, s10, 0
	s_add_u32 s8, s70, s1
	v_mbcnt_hi_u32_b32 v16, s11, v16
	s_addc_u32 s9, s71, 0
	v_cmp_eq_u32_e32 vcc, 0, v16
	s_and_saveexec_b64 s[12:13], vcc
	s_cbranch_execz .LBB0_1403
	s_bcnt1_i32_b64 s1, s[10:11]
	v_mov_b32_e32 v17, 0x1000
	v_mov_b32_e32 v18, s1
	global_atomic_add v17, v17, v18, s[8:9] offset:1024 sc0
.LBB0_1403:
	s_or_b64 exec, exec, s[12:13]
	s_waitcnt vmcnt(0)
	s_cmp_eq_u32 s0, 0
	s_cselect_b64 vcc, -1, 0
	s_cmp_eq_u32 s0, 1
	v_cndmask_b32_e32 v18, 1, v15, vcc
	s_cselect_b64 vcc, -1, 0
	s_cmp_eq_u32 s0, 2
	v_cndmask_b32_e32 v18, v18, v0, vcc
	s_cselect_b64 vcc, -1, 0
	s_cmp_eq_u32 s0, 3
	v_cndmask_b32_e32 v18, v18, v1, vcc
	s_cselect_b64 vcc, -1, 0
	s_cmp_eq_u32 s0, 4
	v_cndmask_b32_e32 v18, v18, v2, vcc
	s_cselect_b64 vcc, -1, 0
	s_cmp_eq_u32 s0, 5
	v_cndmask_b32_e32 v18, v18, v3, vcc
	s_cselect_b64 vcc, -1, 0
	s_cmp_eq_u32 s0, 6
	v_cndmask_b32_e32 v18, v18, v4, vcc
	s_cselect_b64 vcc, -1, 0
	s_cmp_eq_u32 s0, 7
	v_cndmask_b32_e32 v18, v18, v5, vcc
	s_cselect_b64 vcc, -1, 0
	s_cmp_eq_u32 s0, 8
	v_cndmask_b32_e32 v18, v18, v6, vcc
	s_cselect_b64 vcc, -1, 0
	s_cmp_eq_u32 s0, 9
	v_cndmask_b32_e32 v18, v18, v7, vcc
	s_cselect_b64 vcc, -1, 0
	s_cmp_eq_u32 s0, 10
	v_cndmask_b32_e32 v18, v18, v8, vcc
	s_cselect_b64 vcc, -1, 0
	s_cmp_eq_u32 s0, 11
	v_cndmask_b32_e32 v18, v18, v9, vcc
	s_cselect_b64 vcc, -1, 0
	s_cmp_eq_u32 s0, 12
	v_cndmask_b32_e32 v18, v18, v10, vcc
	s_cselect_b64 vcc, -1, 0
	s_cmp_eq_u32 s0, 13
	v_cndmask_b32_e32 v18, v18, v11, vcc
	s_cselect_b64 vcc, -1, 0
	s_cmp_eq_u32 s0, 14
	v_cndmask_b32_e32 v18, v18, v12, vcc
	s_cselect_b64 vcc, -1, 0
	s_cmp_eq_u32 s0, 15
	v_cndmask_b32_e32 v18, v18, v13, vcc
	s_cselect_b64 vcc, -1, 0
	v_cndmask_b32_e32 v18, v18, v14, vcc
	v_cvt_f32_u32_e32 v19, v18
	s_waitcnt vmcnt(0)
	v_readfirstlane_b32 s0, v17
	v_rcp_iflag_f32_e32 v19, v19
	s_nop 0
	v_add_u32_e32 v17, s0, v16
	v_sub_u32_e32 v16, 0, v18
	v_mul_f32_e32 v19, 0x4f7ffffe, v19
	v_cvt_u32_f32_e32 v19, v19
	v_mul_lo_u32 v16, v16, v19
	v_mul_hi_u32 v16, v19, v16
	v_add_u32_e32 v16, v19, v16
	v_mul_hi_u32 v16, v17, v16
	v_mul_lo_u32 v19, v16, v18
	v_sub_u32_e32 v19, v17, v19
	v_add_u32_e32 v20, 1, v16
	v_cmp_ge_u32_e32 vcc, v19, v18
	v_add_u32_e32 v17, 1, v17
	s_nop 0
	v_cndmask_b32_e32 v16, v16, v20, vcc
	v_sub_u32_e32 v20, v19, v18
	v_cndmask_b32_e32 v19, v19, v20, vcc
	v_add_u32_e32 v20, 1, v16
	v_cmp_ge_u32_e32 vcc, v19, v18
	s_nop 1
	v_cndmask_b32_e32 v16, v16, v20, vcc
	v_mul_lo_u32 v19, v18, v16
	v_add_u32_e32 v18, v19, v18
	v_cmp_ne_u32_e32 vcc, v17, v18
	s_and_saveexec_b64 s[0:1], vcc
	s_xor_b64 s[10:11], exec, s[0:1]
	s_cbranch_execz .LBB0_1408
	v_mov_b32_e32 v17, 0x2000
	global_load_dword v17, v17, s[8:9] offset:1024 sc1
	s_add_u32 s12, s8, 0x2400
	s_addc_u32 s13, s9, 0
	s_waitcnt vmcnt(0)
	v_cmp_eq_u32_e32 vcc, v17, v16
	s_and_saveexec_b64 s[14:15], vcc
	s_cbranch_execz .LBB0_1407
	s_mov_b64 s[16:17], 0
	v_mov_b32_e32 v17, 0

.LBB0_1459:
	global_load_dword v15, v16, s[70:71] offset:1024 sc1
	global_load_dword v0, v16, s[70:71] offset:1280 sc1
	global_load_dword v1, v16, s[70:71] offset:1536 sc1
	global_load_dword v2, v16, s[70:71] offset:1792 sc1
	global_load_dword v3, v16, s[70:71] offset:2048 sc1
	global_load_dword v4, v16, s[70:71] offset:2304 sc1
	global_load_dword v5, v16, s[70:71] offset:2560 sc1
	global_load_dword v6, v16, s[70:71] offset:2816 sc1
	global_load_dword v7, v16, s[70:71] offset:3072 sc1
	global_load_dword v8, v16, s[70:71] offset:3328 sc1
	global_load_dword v9, v16, s[70:71] offset:3584 sc1
	global_load_dword v10, v16, s[70:71] offset:3840 sc1
	global_load_dword v11, v16, s[0:1] sc1
	global_load_dword v12, v16, s[6:7] sc1
	global_load_dword v13, v16, s[8:9] sc1
	global_load_dword v14, v16, s[10:11] sc1
	s_mov_b64 s[6:7], exec
	s_and_b32 s5, s5, 15
	s_lshl_b32 s0, s5, 8
	v_mbcnt_lo_u32_b32 v16, s6, 0
	s_add_u32 s0, s70, s0
	v_mbcnt_hi_u32_b32 v16, s7, v16
	s_addc_u32 s1, s71, 0
	v_cmp_eq_u32_e32 vcc, 0, v16
	s_and_saveexec_b64 s[8:9], vcc
	s_cbranch_execz .LBB0_1463
	s_bcnt1_i32_b64 s6, s[6:7]
	v_mov_b32_e32 v17, 0x1000
	v_mov_b32_e32 v18, s6
	global_atomic_add v17, v17, v18, s[0:1] offset:1024 sc0
.LBB0_1463:
	s_or_b64 exec, exec, s[8:9]
	s_waitcnt vmcnt(0)
	s_cmp_eq_u32 s5, 0
	s_cselect_b64 vcc, -1, 0
	s_cmp_eq_u32 s5, 1
	v_cndmask_b32_e32 v18, 1, v15, vcc
	s_cselect_b64 vcc, -1, 0
	s_cmp_eq_u32 s5, 2
	v_cndmask_b32_e32 v18, v18, v0, vcc
	s_cselect_b64 vcc, -1, 0
	s_cmp_eq_u32 s5, 3
	v_cndmask_b32_e32 v18, v18, v1, vcc
	s_cselect_b64 vcc, -1, 0
	s_cmp_eq_u32 s5, 4
	v_cndmask_b32_e32 v18, v18, v2, vcc
	s_cselect_b64 vcc, -1, 0
	s_cmp_eq_u32 s5, 5
	v_cndmask_b32_e32 v18, v18, v3, vcc
	s_cselect_b64 vcc, -1, 0
	s_cmp_eq_u32 s5, 6
	v_cndmask_b32_e32 v18, v18, v4, vcc
	s_cselect_b64 vcc, -1, 0
	s_cmp_eq_u32 s5, 7
	v_cndmask_b32_e32 v18, v18, v5, vcc
	s_cselect_b64 vcc, -1, 0
	s_cmp_eq_u32 s5, 8
	v_cndmask_b32_e32 v18, v18, v6, vcc
	s_cselect_b64 vcc, -1, 0
	s_cmp_eq_u32 s5, 9
	v_cndmask_b32_e32 v18, v18, v7, vcc
	s_cselect_b64 vcc, -1, 0
	s_cmp_eq_u32 s5, 10
	v_cndmask_b32_e32 v18, v18, v8, vcc
	s_cselect_b64 vcc, -1, 0
	s_cmp_eq_u32 s5, 11
	v_cndmask_b32_e32 v18, v18, v9, vcc
	s_cselect_b64 vcc, -1, 0
	s_cmp_eq_u32 s5, 12
	v_cndmask_b32_e32 v18, v18, v10, vcc
	s_cselect_b64 vcc, -1, 0
	s_cmp_eq_u32 s5, 13
	v_cndmask_b32_e32 v18, v18, v11, vcc
	s_cselect_b64 vcc, -1, 0
	s_cmp_eq_u32 s5, 14
	v_cndmask_b32_e32 v18, v18, v12, vcc
	s_cselect_b64 vcc, -1, 0
	s_cmp_eq_u32 s5, 15
	v_cndmask_b32_e32 v18, v18, v13, vcc
	s_cselect_b64 vcc, -1, 0
	v_cndmask_b32_e32 v18, v18, v14, vcc
	v_cvt_f32_u32_e32 v19, v18
	s_waitcnt vmcnt(0)
	v_readfirstlane_b32 s5, v17
	v_rcp_iflag_f32_e32 v19, v19
	s_nop 0
	v_add_u32_e32 v17, s5, v16
	v_sub_u32_e32 v16, 0, v18
	v_mul_f32_e32 v19, 0x4f7ffffe, v19
	v_cvt_u32_f32_e32 v19, v19
	v_mul_lo_u32 v16, v16, v19
	v_mul_hi_u32 v16, v19, v16
	v_add_u32_e32 v16, v19, v16
	v_mul_hi_u32 v16, v17, v16
	v_mul_lo_u32 v19, v16, v18
	v_sub_u32_e32 v19, v17, v19
	v_add_u32_e32 v20, 1, v16
	v_cmp_ge_u32_e32 vcc, v19, v18
	v_add_u32_e32 v17, 1, v17
	s_nop 0
	v_cndmask_b32_e32 v16, v16, v20, vcc
	v_sub_u32_e32 v20, v19, v18
	v_cndmask_b32_e32 v19, v19, v20, vcc
	v_add_u32_e32 v20, 1, v16
	v_cmp_ge_u32_e32 vcc, v19, v18
	s_nop 1
	v_cndmask_b32_e32 v16, v16, v20, vcc
	v_mul_lo_u32 v19, v18, v16
	v_add_u32_e32 v18, v19, v18
	v_cmp_ne_u32_e32 vcc, v17, v18
	s_and_saveexec_b64 s[6:7], vcc
	s_xor_b64 s[6:7], exec, s[6:7]
	s_cbranch_execz .LBB0_1468
	v_mov_b32_e32 v17, 0x2000
	global_load_dword v17, v17, s[0:1] offset:1024 sc1
	s_add_u32 s8, s0, 0x2400
	s_addc_u32 s9, s1, 0
	s_waitcnt vmcnt(0)
	v_cmp_eq_u32_e32 vcc, v17, v16
	s_and_saveexec_b64 s[10:11], vcc
	s_cbranch_execz .LBB0_1467
	s_mov_b64 s[12:13], 0
	v_mov_b32_e32 v17, 0
